# attention QK segments: one LDS wait per K-fragment pair instead of two (16 fewer s_waitcnt per loop trip)
# baseline (speedup 1.0000x reference)
; #define SBAR() __builtin_amdgcn_sched_barrier(0)
; #define SLOAD(i, k0) do { sr_[i].vs0 = St::ld8(&Vh[(long)((k0) + sr) * LDK + sc]); sr_[i].vs1 = St::ld8(&Vh[(long)((k0) + 32 + sr) * LDK + sc]); \
;     sr_[i].ks0 = St::ld8(&Kh[(long)((k0) + sr) * LDK + sc]); sr_[i].ks1 = St::ld8(&Kh[(long)((k0) + 32 + sr) * LDK + sc]); } while (0)
; __device__ __forceinline__ void finishSM(f32x16& p0, f32x16& p1, float alpha, float& l_reg, bf16x8& pa0, bf16x8& pa1, bf16x8& pa2, bf16x8& pa3) {
;   for (int r = 0; r < 16; ++r) p1[r] = __builtin_amdgcn_exp2f(p1[r]);
;   float ps = 0; for (int r = 0; r < 16; ++r) ps += p0[r]; for (int r = 0; r < 16; ++r) ps += p1[r];
;   { auto rr = __builtin_amdgcn_permlane32_swap(__float_as_uint(ps), __float_as_uint(ps), false, false);
;     ps = __uint_as_float(rr[0]) + __uint_as_float(rr[1]); }
;   l_reg = l_reg * alpha + ps;
;     ...
;   PK4(p0, 0, pa0); PK4(p0, 8, pa1); PK4(p1, 0, pa2); PK4(p1, 8, pa3);
;     ...
; }
; __device__ __forceinline__ void qkt(f32x16& p0, f32x16& p1, const bf16* Ks, const bf16x8* qr, int r32, int hi) {
;   p0 = f32x16{}; p1 = f32x16{};
;   for (int d0 = 0; d0 < 8; ++d0) { int cb = (d0 * 16 + hi * 8) * 2;
;     bf16x8 b0 = *reinterpret_cast<const bf16x8*>((const char*)Ks + KSWZ(r32, cb));
;     bf16x8 b1 = *reinterpret_cast<const bf16x8*>((const char*)Ks + KSWZ(32 + r32, cb));
;     p0 = __builtin_amdgcn_mfma_f32_32x32x16_bf16(b0, qr[d0], p0, 0, 0, 0);
;     p1 = __builtin_amdgcn_mfma_f32_32x32x16_bf16(b1, qr[d0], p1, 0, 0, 0); }
; template <typename TQ>
; __device__ __forceinline__ void attn_dense_body(const TQ* __restrict__ Qb, const bf16* __restrict__ Kh, const bf16* __restrict__ Vh,
;                                                 unsigned short* __restrict__ Ob, int seq, char* lds) {
;     ...
;     SBAR(); qkt(pB0, pB1, (bf16*)((char*)K_lds + SHM_K), qr, r32, hi);
;     finishSM(pA0, pA1, alA, l_reg, pa0, pa1, pa2, pa3); SBAR();
;     SLOAD(SO, (j + SDEPTH) * KVBLK); SBAR();
;     pv_d0(o, vb0, pa0, pa1, pa2, pa3); partialSM(pB0, pB1, m_reg, mnB, alB);
.LBB0_1586:
	ds_read_b128 v[66:69], v195 offset:49152
	ds_read_b128 v[70:73], v195 offset:57344
	ds_read_b128 v[228:231], v196 offset:49152
	ds_read_b128 v[232:235], v196 offset:57344
	v_add_f32_e32 v162, 0, v224
	v_add_f32_e32 v162, v226, v162
	v_add_f32_e32 v162, v222, v162
	v_add_f32_e32 v162, v225, v162
	v_add_f32_e32 v162, v164, v162
	s_waitcnt lgkmcnt(2)
	v_mfma_f32_32x32x16_bf16 v[82:97], v[66:69], v[126:129], 0
	v_add_f32_e32 v162, v223, v162
	v_add_f32_e32 v162, v220, v162
	v_add_f32_e32 v162, v221, v162
	v_add_f32_e32 v162, v217, v162
	v_add_f32_e32 v162, v219, v162
	v_mfma_f32_32x32x16_bf16 v[66:81], v[70:73], v[126:129], 0
	v_add_f32_e32 v162, v216, v162
	v_add_f32_e32 v162, v218, v162
	v_exp_f32_e32 v156, v156
	v_add_f32_e32 v162, v213, v162
	v_exp_f32_e32 v157, v157
	s_waitcnt lgkmcnt(0)
	v_mfma_f32_32x32x16_bf16 v[82:97], v[228:231], v[122:125], v[82:97]
	v_add_f32_e32 v162, v215, v162
	v_exp_f32_e32 v154, v154
	v_add_f32_e32 v162, v212, v162
	v_exp_f32_e32 v155, v155
	v_add_f32_e32 v162, v214, v162
	v_mfma_f32_32x32x16_bf16 v[66:81], v[232:235], v[122:125], v[66:81]
	ds_read_b128 v[228:231], v197 offset:49152
	ds_read_b128 v[232:235], v197 offset:57344
	v_exp_f32_e32 v150, v150
	v_add_f32_e32 v162, v156, v162
	v_exp_f32_e32 v151, v151
	v_add_f32_e32 v162, v157, v162
	v_exp_f32_e32 v148, v148
	s_waitcnt lgkmcnt(0)
	v_mfma_f32_32x32x16_bf16 v[82:97], v[228:231], v[118:121], v[82:97]
	v_add_f32_e32 v162, v154, v162
	v_exp_f32_e32 v149, v149
	v_add_f32_e32 v162, v155, v162
	v_exp_f32_e32 v146, v146
	v_add_f32_e32 v162, v150, v162
	v_mfma_f32_32x32x16_bf16 v[66:81], v[232:235], v[118:121], v[66:81]
	ds_read_b128 v[228:231], v198 offset:49152
	ds_read_b128 v[232:235], v198 offset:57344
	v_exp_f32_e32 v147, v147
	v_add_f32_e32 v162, v151, v162
	v_exp_f32_e32 v160, v160
	v_add_f32_e32 v162, v148, v162
	v_exp_f32_e32 v161, v161
	s_waitcnt lgkmcnt(0)
	v_mfma_f32_32x32x16_bf16 v[82:97], v[228:231], v[114:117], v[82:97]
	v_add_f32_e32 v162, v149, v162
	v_exp_f32_e32 v158, v158
	v_add_f32_e32 v162, v146, v162
	v_exp_f32_e32 v159, v159
	v_add_f32_e32 v162, v147, v162
	v_mfma_f32_32x32x16_bf16 v[66:81], v[232:235], v[114:117], v[66:81]
	ds_read_b128 v[228:231], v199 offset:49152
	ds_read_b128 v[232:235], v199 offset:57344
	v_exp_f32_e32 v152, v152
	v_add_f32_e32 v162, v160, v162
	v_exp_f32_e32 v153, v153
	v_add_f32_e32 v162, v161, v162
	v_add_f32_e32 v162, v158, v162
	s_waitcnt lgkmcnt(0)
	v_mfma_f32_32x32x16_bf16 v[82:97], v[228:231], v[110:113], v[82:97]
	v_add_f32_e32 v162, v159, v162
	v_add_f32_e32 v162, v152, v162
	v_add_f32_e32 v209, v153, v162
	v_mov_b32_e32 v210, v209
	s_nop 1
	v_permlane32_swap_b32_e32 v209, v210
	v_mfma_f32_32x32x16_bf16 v[66:81], v[232:235], v[110:113], v[66:81]
	ds_read_b128 v[228:231], v200 offset:49152
	ds_read_b128 v[232:235], v200 offset:57344
	v_cvt_pk_bf16_f32 v162, v224, v226
	v_cvt_pk_bf16_f32 v163, v222, v225
	v_cvt_pk_bf16_f32 v164, v164, v223
	v_cvt_pk_bf16_f32 v165, v220, v221
	v_cvt_pk_bf16_f32 v220, v217, v219
	s_waitcnt lgkmcnt(0)
	v_mfma_f32_32x32x16_bf16 v[82:97], v[228:231], v[106:109], v[82:97]
	v_cvt_pk_bf16_f32 v221, v216, v218
	v_permlane32_swap_b32_e32 v162, v164
	v_permlane32_swap_b32_e32 v163, v165
	v_cvt_pk_bf16_f32 v222, v213, v215
	v_cvt_pk_bf16_f32 v223, v212, v214
	v_mfma_f32_32x32x16_bf16 v[66:81], v[232:235], v[106:109], v[66:81]
	ds_read_b128 v[228:231], v201 offset:49152
	ds_read_b128 v[232:235], v201 offset:57344
	v_cvt_pk_bf16_f32 v212, v156, v157
	v_cvt_pk_bf16_f32 v213, v154, v155
	v_cvt_pk_bf16_f32 v214, v150, v151
	v_cvt_pk_bf16_f32 v215, v148, v149
	v_cvt_pk_bf16_f32 v216, v146, v147
	s_waitcnt lgkmcnt(0)
	v_mfma_f32_32x32x16_bf16 v[82:97], v[228:231], v[102:105], v[82:97]
	v_cvt_pk_bf16_f32 v217, v160, v161
	v_cvt_pk_bf16_f32 v218, v158, v159
	v_cvt_pk_bf16_f32 v219, v152, v153
	v_permlane32_swap_b32_e32 v220, v222
	v_permlane32_swap_b32_e32 v221, v223
	v_mfma_f32_32x32x16_bf16 v[66:81], v[232:235], v[102:105], v[66:81]
	ds_read_b128 v[228:231], v202 offset:49152
	ds_read_b128 v[232:235], v202 offset:57344
	v_permlane32_swap_b32_e32 v212, v214
	v_permlane32_swap_b32_e32 v213, v215
	v_permlane32_swap_b32_e32 v216, v218
	v_permlane32_swap_b32_e32 v217, v219
	s_waitcnt lgkmcnt(0)
	v_mfma_f32_32x32x16_bf16 v[82:97], v[228:231], v[98:101], v[82:97]
	v_mfma_f32_32x32x16_bf16 v[66:81], v[232:235], v[98:101], v[66:81]
	s_add_u32 s98, s38, s49
	s_addc_u32 s99, s39, 0
	s_add_u32 s100, s38, s52
	s_addc_u32 s101, s39, 0
	global_load_dwordx4 v[146:149], v170, s[98:99]
	global_load_dwordx4 v[150:153], v172, s[98:99]
	global_load_dwordx4 v[154:157], v170, s[100:101]
	global_load_dwordx4 v[158:161], v172, s[100:101]
	ds_read_b64_tr_b16 v[224:225], v185 offset:0
	ds_read_b64_tr_b16 v[226:227], v185 offset:0x800
	ds_read_b64_tr_b16 v[228:229], v185 offset:0x1000
	ds_read_b64_tr_b16 v[230:231], v185 offset:0x1800
	ds_read_b64_tr_b16 v[232:233], v185 offset:0x2000
	ds_read_b64_tr_b16 v[234:235], v185 offset:0x2800
	ds_read_b64_tr_b16 v[236:237], v185 offset:0x3000
	ds_read_b64_tr_b16 v[238:239], v185 offset:0x3800
	s_waitcnt lgkmcnt(0)
; #define SBAR() __builtin_amdgcn_sched_barrier(0)
; #define SWAIT() do { if constexpr (SDEPTH == 2) asm volatile("s_waitcnt vmcnt(4)" ::: "memory"); else asm volatile("s_waitcnt vmcnt(0)" ::: "memory"); } while (0)
; #define RESC(a) do { if (__any((a) < 1.f)) { if (hi == 0) al_l[r32] = (a); asm volatile("s_waitcnt lgkmcnt(0)" ::: "memory"); \
;     for (int d = 0; d < 4; ++d) for (int r = 0; r < 16; ++r) o[d][r] *= al_l[crow(r, hi)]; } } while (0)
; template <int OFF> __device__ __forceinline__ s16x4 tr_read(int vb) {
;   s16x4 r; asm volatile("ds_read_b64_tr_b16 %0, %1 offset:%2" : "=&v"(r) : "v"(vb), "i"(OFF) : "memory"); return r;
; }
; template <int D0> __device__ __forceinline__ void pv_one(f32x16& od, int vb, bf16x8 pa0, bf16x8 pa1, bf16x8 pa2, bf16x8 pa3) {
;   const s16x4 l0 = tr_read<v_rd_off(D0, 0, 0)>(vb), h0 = tr_read<v_rd_off(D0, 0, 1)>(vb), l1 = tr_read<v_rd_off(D0, 1, 0)>(vb), h1 = tr_read<v_rd_off(D0, 1, 1)>(vb);
;   const s16x4 l2 = tr_read<v_rd_off(D0, 2, 0)>(vb), h2 = tr_read<v_rd_off(D0, 2, 1)>(vb), l3 = tr_read<v_rd_off(D0, 3, 0)>(vb), h3 = tr_read<v_rd_off(D0, 3, 1)>(vb);
;   asm volatile("s_waitcnt lgkmcnt(0)" ::: "memory"); SBAR();
;     ...
;   od = __builtin_amdgcn_mfma_f32_32x32x16_bf16(pa0, PK(l0, h0), od, 0, 0, 0);
;   od = __builtin_amdgcn_mfma_f32_32x32x16_bf16(pa1, PK(l1, h1), od, 0, 0, 0);
;   od = __builtin_amdgcn_mfma_f32_32x32x16_bf16(pa2, PK(l2, h2), od, 0, 0, 0);
;   od = __builtin_amdgcn_mfma_f32_32x32x16_bf16(pa3, PK(l3, h3), od, 0, 0, 0);
;     ...
; }
; __device__ __forceinline__ void pv_d0(f32x16* o, int vb, bf16x8 pa0, bf16x8 pa1, bf16x8 pa2, bf16x8 pa3) {
;   pv_one<0>(o[0], vb, pa0, pa1, pa2, pa3); pv_one<1>(o[1], vb, pa0, pa1, pa2, pa3); pv_one<2>(o[2], vb, pa0, pa1, pa2, pa3); pv_one<3>(o[3], vb, pa0, pa1, pa2, pa3);
; template <typename TQ>
; __device__ __forceinline__ void attn_dense_body(const TQ* __restrict__ Qb, const bf16* __restrict__ Kh, const bf16* __restrict__ Vh,
;                                                 unsigned short* __restrict__ Ob, int seq, char* lds) {
;     ...
;     pv_d0(o, vb0, pa0, pa1, pa2, pa3); partialSM(pB0, pB1, m_reg, mnB, alB);
;     __syncthreads(); SWAIT(); SWRITE(0, SE);
;     RESC(alB); __syncthreads();
	s_nop 0
	v_mfma_f32_32x32x16_bf16 v[2:17], v[162:165], v[224:227], v[2:17]
	v_max_f32_e32 v248, v83, v83
	v_max_f32_e32 v249, v82, v82
	v_max_f32_e32 v248, v249, v248
	v_max3_f32 v248, v248, v84, v85
	v_max3_f32 v248, v248, v86, v87
	ds_read_b64_tr_b16 v[224:225], v185 offset:0x200
	ds_read_b64_tr_b16 v[226:227], v185 offset:0xa00
	v_mfma_f32_32x32x16_bf16 v[2:17], v[220:223], v[228:231], v[2:17]
	v_max3_f32 v248, v248, v88, v89
	v_max3_f32 v248, v248, v90, v91
	v_max3_f32 v248, v248, v92, v93
	v_max3_f32 v248, v248, v94, v95
	v_max3_f32 v248, v248, v96, v97
	ds_read_b64_tr_b16 v[228:229], v185 offset:0x1200
	ds_read_b64_tr_b16 v[230:231], v185 offset:0x1a00
	v_mfma_f32_32x32x16_bf16 v[2:17], v[212:215], v[232:235], v[2:17]
	v_max3_f32 v248, v248, v66, v67
	v_max3_f32 v248, v248, v68, v69
	v_max3_f32 v248, v248, v70, v71
	v_max3_f32 v248, v248, v72, v73
	v_max3_f32 v248, v248, v74, v75
	ds_read_b64_tr_b16 v[232:233], v185 offset:0x2200
	ds_read_b64_tr_b16 v[234:235], v185 offset:0x2a00
	ds_read_b64_tr_b16 v[240:241], v185 offset:0x3200
	ds_read_b64_tr_b16 v[242:243], v185 offset:0x3a00
	s_waitcnt lgkmcnt(0)
	v_mfma_f32_32x32x16_bf16 v[2:17], v[216:219], v[236:239], v[2:17]
	v_max3_f32 v248, v248, v76, v77
	v_max3_f32 v248, v248, v78, v79
	v_max3_f32 v248, v248, v80, v81
	v_mov_b32_e32 v249, v248
	s_nop 1
	v_mfma_f32_32x32x16_bf16 v[18:33], v[162:165], v[224:227], v[18:33]
	v_permlane32_swap_b32_e32 v248, v249
	v_max_f32_e32 v249, v249, v249
	v_max_f32_e32 v248, v248, v248
	v_max_f32_e32 v248, v248, v249
	v_max_f32_e32 v250, v208, v208
	ds_read_b64_tr_b16 v[224:225], v185 offset:0x400
	ds_read_b64_tr_b16 v[226:227], v185 offset:0xc00
	v_mfma_f32_32x32x16_bf16 v[18:33], v[220:223], v[228:231], v[18:33]
	v_sub_f32_e32 v249, v248, v208
	v_max_f32_e32 v248, v250, v248
	v_sub_f32_e32 v250, v208, v248
	v_mul_f32_e32 v250, 0x3e0293ee, v250
	v_exp_f32_e32 v250, v250
	ds_read_b64_tr_b16 v[228:229], v185 offset:0x1400
	ds_read_b64_tr_b16 v[230:231], v185 offset:0x1c00
	v_mfma_f32_32x32x16_bf16 v[18:33], v[212:215], v[232:235], v[18:33]
	v_cmp_ge_f32_e32 vcc, s48, v249
	s_cmp_eq_u64 vcc, exec
	s_cselect_b64 s[4:5], -1, 0
	ds_read_b64_tr_b16 v[232:233], v185 offset:0x2400
	ds_read_b64_tr_b16 v[234:235], v185 offset:0x2c00
	ds_read_b64_tr_b16 v[236:237], v185 offset:0x3400
	ds_read_b64_tr_b16 v[238:239], v185 offset:0x3c00
	s_waitcnt lgkmcnt(0)
	v_mfma_f32_32x32x16_bf16 v[18:33], v[216:219], v[240:243], v[18:33]
	v_cndmask_b32_e64 v249, v250, 1.0, s[4:5]
	v_cndmask_b32_e64 v251, v248, v208, s[4:5]
	v_mul_f32_e32 v248, 0xbe0293ee, v251
	v_mfma_f32_32x32x16_bf16 v[50:65], v[162:165], v[224:227], v[50:65]
	v_fmamk_f32 v82, v82, 0x3e0293ee, v248
	v_fmamk_f32 v83, v83, 0x3e0293ee, v248
	v_fmamk_f32 v84, v84, 0x3e0293ee, v248
	ds_read_b64_tr_b16 v[224:225], v185 offset:0x600
	ds_read_b64_tr_b16 v[226:227], v185 offset:0xe00
	v_mfma_f32_32x32x16_bf16 v[50:65], v[220:223], v[228:231], v[50:65]
	v_fmamk_f32 v85, v85, 0x3e0293ee, v248
	v_fmamk_f32 v86, v86, 0x3e0293ee, v248
	v_fmamk_f32 v87, v87, 0x3e0293ee, v248
	ds_read_b64_tr_b16 v[228:229], v185 offset:0x1600
	ds_read_b64_tr_b16 v[230:231], v185 offset:0x1e00
	v_mfma_f32_32x32x16_bf16 v[50:65], v[212:215], v[232:235], v[50:65]
	v_fmamk_f32 v88, v88, 0x3e0293ee, v248
	v_fmamk_f32 v89, v89, 0x3e0293ee, v248
	ds_read_b64_tr_b16 v[232:233], v185 offset:0x2600
	ds_read_b64_tr_b16 v[234:235], v185 offset:0x2e00
	ds_read_b64_tr_b16 v[240:241], v185 offset:0x3600
	ds_read_b64_tr_b16 v[242:243], v185 offset:0x3e00
	s_waitcnt lgkmcnt(0)
	v_mfma_f32_32x32x16_bf16 v[50:65], v[216:219], v[236:239], v[50:65]
	v_fmamk_f32 v90, v90, 0x3e0293ee, v248
	v_fmamk_f32 v91, v91, 0x3e0293ee, v248
	v_mfma_f32_32x32x16_bf16 v[34:49], v[162:165], v[224:227], v[34:49]
	v_fmamk_f32 v92, v92, 0x3e0293ee, v248
	v_fmamk_f32 v93, v93, 0x3e0293ee, v248
	v_mfma_f32_32x32x16_bf16 v[34:49], v[220:223], v[228:231], v[34:49]
	v_fmamk_f32 v94, v94, 0x3e0293ee, v248
	v_fmamk_f32 v95, v95, 0x3e0293ee, v248
	v_mfma_f32_32x32x16_bf16 v[34:49], v[212:215], v[232:235], v[34:49]
	v_fmamk_f32 v96, v96, 0x3e0293ee, v248
	v_fmamk_f32 v97, v97, 0x3e0293ee, v248
	v_mfma_f32_32x32x16_bf16 v[34:49], v[216:219], v[240:243], v[34:49]
	s_barrier
	s_waitcnt vmcnt(4)
	v_mov_b32_e32 v163, v249
	v_mov_b32_e32 v164, v251
	v_mov_b32_e32 v162, v248
	v_cmp_gt_f32_e32 vcc, 1.0, v163
	s_waitcnt vmcnt(7)
	ds_write_b128 v191, v[130:133]
	s_waitcnt vmcnt(5)
	ds_write_b128 v192, v[142:145]
	ds_write_b128 v193, v[134:137] offset:32768
	s_waitcnt vmcnt(4)
	ds_write_b128 v194, v[138:141] offset:32768
	s_cbranch_vccz .LBB0_1590
	s_and_saveexec_b64 s[40:41], s[2:3]
	ds_write_b32 v187, v163 offset:128
	s_or_b64 exec, exec, s[40:41]
	s_waitcnt lgkmcnt(0)
	v_add_u32_e32 v142, v182, v186
	ds_read_b128 v[130:133], v142 offset:224
	ds_read_b128 v[134:137], v142 offset:192
	ds_read_b128 v[138:141], v142 offset:160
	ds_read_b128 v[142:145], v142 offset:128
	s_waitcnt lgkmcnt(3)
	v_pk_mul_f32 v[14:15], v[14:15], v[130:131]
	s_waitcnt lgkmcnt(2)
	v_pk_mul_f32 v[10:11], v[10:11], v[134:135]
	s_waitcnt lgkmcnt(1)
	v_pk_mul_f32 v[6:7], v[6:7], v[138:139]
	v_pk_mul_f32 v[16:17], v[16:17], v[132:133]
	v_pk_mul_f32 v[12:13], v[12:13], v[136:137]
	v_pk_mul_f32 v[8:9], v[8:9], v[140:141]
	s_waitcnt lgkmcnt(0)
	v_pk_mul_f32 v[4:5], v[4:5], v[144:145]
	v_pk_mul_f32 v[2:3], v[2:3], v[142:143]
	v_pk_mul_f32 v[30:31], v[30:31], v[130:131]
	v_pk_mul_f32 v[26:27], v[26:27], v[134:135]
	v_pk_mul_f32 v[22:23], v[22:23], v[138:139]
	v_pk_mul_f32 v[32:33], v[32:33], v[132:133]
	v_pk_mul_f32 v[28:29], v[28:29], v[136:137]
	v_pk_mul_f32 v[24:25], v[24:25], v[140:141]
	v_pk_mul_f32 v[20:21], v[20:21], v[144:145]
	v_pk_mul_f32 v[18:19], v[18:19], v[142:143]
	v_pk_mul_f32 v[62:63], v[62:63], v[130:131]
	v_pk_mul_f32 v[58:59], v[58:59], v[134:135]
	v_pk_mul_f32 v[54:55], v[54:55], v[138:139]
	v_pk_mul_f32 v[64:65], v[64:65], v[132:133]
	v_pk_mul_f32 v[60:61], v[60:61], v[136:137]
	v_pk_mul_f32 v[56:57], v[56:57], v[140:141]
	v_pk_mul_f32 v[52:53], v[52:53], v[144:145]
	v_pk_mul_f32 v[50:51], v[50:51], v[142:143]
	v_pk_mul_f32 v[46:47], v[46:47], v[130:131]
	v_pk_mul_f32 v[42:43], v[42:43], v[134:135]
	v_pk_mul_f32 v[38:39], v[38:39], v[138:139]
	v_pk_mul_f32 v[48:49], v[48:49], v[132:133]
	v_pk_mul_f32 v[44:45], v[44:45], v[136:137]
	v_pk_mul_f32 v[40:41], v[40:41], v[140:141]
	v_pk_mul_f32 v[36:37], v[36:37], v[144:145]
	v_pk_mul_f32 v[34:35], v[34:35], v[142:143]
; #define SBAR() __builtin_amdgcn_sched_barrier(0)
; #define RESC(a) do { if (__any((a) < 1.f)) { if (hi == 0) al_l[r32] = (a); asm volatile("s_waitcnt lgkmcnt(0)" ::: "memory"); \
;     for (int d = 0; d < 4; ++d) for (int r = 0; r < 16; ++r) o[d][r] *= al_l[crow(r, hi)]; } } while (0)
; __device__ __forceinline__ void partialSM(f32x16& p0, f32x16& p1, float& m_reg, float& mn, float& alpha) {
;     ...
;   for (int r = 0; r < 16; ++r) p0[r] = fmaf(p0[r], C, mnC); for (int r = 0; r < 16; ++r) p1[r] = fmaf(p1[r], C, mnC);
;   for (int r = 0; r < 16; ++r) p0[r] = __builtin_amdgcn_exp2f(p0[r]);
; }
; __device__ __forceinline__ void finishSM(f32x16& p0, f32x16& p1, float alpha, float& l_reg, bf16x8& pa0, bf16x8& pa1, bf16x8& pa2, bf16x8& pa3) {
;   for (int r = 0; r < 16; ++r) p1[r] = __builtin_amdgcn_exp2f(p1[r]);
;   float ps = 0; for (int r = 0; r < 16; ++r) ps += p0[r]; for (int r = 0; r < 16; ++r) ps += p1[r];
;   { auto rr = __builtin_amdgcn_permlane32_swap(__float_as_uint(ps), __float_as_uint(ps), false, false);
;     ps = __uint_as_float(rr[0]) + __uint_as_float(rr[1]); }
;   l_reg = l_reg * alpha + ps;
;     ...
;   PK4(p0, 0, pa0); PK4(p0, 8, pa1); PK4(p1, 0, pa2); PK4(p1, 8, pa3);
;     ...
; }
; __device__ __forceinline__ void qkt(f32x16& p0, f32x16& p1, const bf16* Ks, const bf16x8* qr, int r32, int hi) {
;   p0 = f32x16{}; p1 = f32x16{};
;   for (int d0 = 0; d0 < 8; ++d0) { int cb = (d0 * 16 + hi * 8) * 2;
;     bf16x8 b0 = *reinterpret_cast<const bf16x8*>((const char*)Ks + KSWZ(r32, cb));
;     bf16x8 b1 = *reinterpret_cast<const bf16x8*>((const char*)Ks + KSWZ(32 + r32, cb));
;     p0 = __builtin_amdgcn_mfma_f32_32x32x16_bf16(b0, qr[d0], p0, 0, 0, 0);
;     p1 = __builtin_amdgcn_mfma_f32_32x32x16_bf16(b1, qr[d0], p1, 0, 0, 0); }
; template <typename TQ>
; __device__ __forceinline__ void attn_dense_body(const TQ* __restrict__ Qb, const bf16* __restrict__ Kh, const bf16* __restrict__ Vh,
;                                                 unsigned short* __restrict__ Ob, int seq, char* lds) {
;     ...
;     RESC(alB); __syncthreads();
;     SBAR(); qkt(pA0, pA1, K_lds, qr, r32, hi);
;     finishSM(pB0, pB1, alB, l_reg, pa0, pa1, pa2, pa3); SBAR();
.LBB0_1590:
	v_exp_f32_e32 v143, v82
	v_exp_f32_e32 v145, v83
	v_exp_f32_e32 v141, v84
	v_exp_f32_e32 v144, v85
	v_exp_f32_e32 v140, v86
	v_exp_f32_e32 v142, v87
	v_exp_f32_e32 v138, v88
	v_exp_f32_e32 v139, v89
	v_exp_f32_e32 v135, v90
	v_exp_f32_e32 v137, v91
	v_exp_f32_e32 v134, v92
	v_exp_f32_e32 v136, v93
	v_exp_f32_e32 v131, v94
	v_exp_f32_e32 v133, v95
	v_exp_f32_e32 v130, v96
	v_exp_f32_e32 v132, v97
	v_fmamk_f32 v217, v66, 0x3e0293ee, v162
	v_fmamk_f32 v218, v67, 0x3e0293ee, v162
	v_fmamk_f32 v219, v68, 0x3e0293ee, v162
	v_fmamk_f32 v220, v69, 0x3e0293ee, v162
	v_fmamk_f32 v221, v70, 0x3e0293ee, v162
	v_fmamk_f32 v208, v71, 0x3e0293ee, v162
	v_fmamk_f32 v211, v72, 0x3e0293ee, v162
	v_fmamk_f32 v212, v73, 0x3e0293ee, v162
	v_fmamk_f32 v213, v74, 0x3e0293ee, v162
	v_fmamk_f32 v214, v75, 0x3e0293ee, v162
	v_fmamk_f32 v215, v76, 0x3e0293ee, v162
	v_fmamk_f32 v216, v77, 0x3e0293ee, v162
	v_fmamk_f32 v165, v78, 0x3e0293ee, v162
	v_fmamk_f32 v222, v79, 0x3e0293ee, v162
	v_fmamk_f32 v223, v80, 0x3e0293ee, v162
	v_fmac_f32_e32 v162, 0x3e0293ee, v81
	s_waitcnt lgkmcnt(0)
	s_barrier
	ds_read_b128 v[66:69], v195 offset:32768
	ds_read_b128 v[70:73], v195 offset:40960
	ds_read_b128 v[224:227], v196 offset:32768
	ds_read_b128 v[228:231], v196 offset:40960
	v_exp_f32_e32 v235, v165
	v_add_f32_e32 v165, 0, v143
	v_add_f32_e32 v165, v145, v165
	v_add_f32_e32 v165, v141, v165
	v_add_f32_e32 v165, v144, v165
	s_waitcnt lgkmcnt(2)
	v_mfma_f32_32x32x16_bf16 v[82:97], v[66:69], v[126:129], 0
	v_add_f32_e32 v165, v140, v165
	v_add_f32_e32 v165, v142, v165
	v_add_f32_e32 v165, v138, v165
	v_add_f32_e32 v165, v139, v165
	v_add_f32_e32 v165, v135, v165
	v_mfma_f32_32x32x16_bf16 v[66:81], v[70:73], v[126:129], 0
	v_add_f32_e32 v165, v137, v165
	v_add_f32_e32 v165, v134, v165
	v_add_f32_e32 v165, v136, v165
	v_add_f32_e32 v165, v131, v165
	v_add_f32_e32 v165, v133, v165
	s_waitcnt lgkmcnt(0)
	v_mfma_f32_32x32x16_bf16 v[82:97], v[224:227], v[122:125], v[82:97]
	v_add_f32_e32 v165, v130, v165
	v_add_f32_e32 v165, v132, v165
	v_exp_f32_e32 v208, v208
	v_exp_f32_e32 v232, v214
	v_exp_f32_e32 v233, v215
	v_mfma_f32_32x32x16_bf16 v[66:81], v[228:231], v[122:125], v[66:81]
	ds_read_b128 v[224:227], v197 offset:32768
	ds_read_b128 v[228:231], v197 offset:40960
	v_exp_f32_e32 v234, v216
	v_exp_f32_e32 v236, v222
	v_exp_f32_e32 v237, v223
	v_exp_f32_e32 v162, v162
	v_exp_f32_e32 v238, v217
	s_waitcnt lgkmcnt(0)
	v_mfma_f32_32x32x16_bf16 v[82:97], v[224:227], v[118:121], v[82:97]
	v_exp_f32_e32 v239, v218
	v_exp_f32_e32 v240, v219
	v_exp_f32_e32 v241, v220
	v_add_f32_e32 v165, v238, v165
	v_add_f32_e32 v165, v239, v165
	v_mfma_f32_32x32x16_bf16 v[66:81], v[228:231], v[118:121], v[66:81]
	ds_read_b128 v[224:227], v198 offset:32768
	ds_read_b128 v[228:231], v198 offset:40960
	v_add_f32_e32 v165, v240, v165
	v_exp_f32_e32 v242, v221
	v_exp_f32_e32 v243, v211
	v_exp_f32_e32 v244, v212
	v_add_f32_e32 v165, v241, v165
	s_waitcnt lgkmcnt(0)
	v_mfma_f32_32x32x16_bf16 v[82:97], v[224:227], v[114:117], v[82:97]
	v_exp_f32_e32 v245, v213
	v_add_f32_e32 v165, v242, v165
	v_add_f32_e32 v165, v208, v165
	v_add_f32_e32 v165, v243, v165
	v_add_f32_e32 v165, v244, v165
	v_mfma_f32_32x32x16_bf16 v[66:81], v[228:231], v[114:117], v[66:81]
	ds_read_b128 v[224:227], v199 offset:32768
	ds_read_b128 v[228:231], v199 offset:40960
	v_add_f32_e32 v165, v245, v165
	v_add_f32_e32 v165, v232, v165
	v_add_f32_e32 v165, v233, v165
	v_add_f32_e32 v165, v234, v165
	v_add_f32_e32 v165, v235, v165
	s_waitcnt lgkmcnt(0)
	v_mfma_f32_32x32x16_bf16 v[82:97], v[224:227], v[110:113], v[82:97]
	v_add_f32_e32 v165, v236, v165
	v_add_f32_e32 v165, v237, v165
	v_add_f32_e32 v165, v162, v165
	v_mov_b32_e32 v211, v165
	s_nop 1
	v_permlane32_swap_b32_e32 v165, v211
	v_mfma_f32_32x32x16_bf16 v[66:81], v[228:231], v[110:113], v[66:81]
	ds_read_b128 v[224:227], v200 offset:32768
	ds_read_b128 v[228:231], v200 offset:40960
	v_cvt_pk_bf16_f32 v212, v143, v145
	v_cvt_pk_bf16_f32 v213, v141, v144
	v_cvt_pk_bf16_f32 v214, v140, v142
	v_cvt_pk_bf16_f32 v215, v138, v139
	v_cvt_pk_bf16_f32 v216, v135, v137
	s_waitcnt lgkmcnt(0)
	v_mfma_f32_32x32x16_bf16 v[82:97], v[224:227], v[106:109], v[82:97]
	v_cvt_pk_bf16_f32 v217, v134, v136
	v_cvt_pk_bf16_f32 v218, v131, v133
	v_cvt_pk_bf16_f32 v219, v130, v132
	v_cvt_pk_bf16_f32 v220, v238, v239
	v_cvt_pk_bf16_f32 v221, v240, v241
	v_mfma_f32_32x32x16_bf16 v[66:81], v[228:231], v[106:109], v[66:81]
	ds_read_b128 v[224:227], v201 offset:32768
	ds_read_b128 v[228:231], v201 offset:40960
	v_cvt_pk_bf16_f32 v222, v242, v208
	v_cvt_pk_bf16_f32 v223, v243, v244
	v_cvt_pk_bf16_f32 v248, v245, v232
	v_cvt_pk_bf16_f32 v249, v233, v234
	v_cvt_pk_bf16_f32 v250, v235, v236
	s_waitcnt lgkmcnt(0)
	v_mfma_f32_32x32x16_bf16 v[82:97], v[224:227], v[102:105], v[82:97]
	v_cvt_pk_bf16_f32 v251, v237, v162
	s_nop 0
	v_permlane32_swap_b32_e32 v212, v214
	v_permlane32_swap_b32_e32 v213, v215
	v_permlane32_swap_b32_e32 v216, v218
	v_permlane32_swap_b32_e32 v217, v219
	v_mfma_f32_32x32x16_bf16 v[66:81], v[228:231], v[102:105], v[66:81]
	ds_read_b128 v[224:227], v202 offset:32768
	ds_read_b128 v[228:231], v202 offset:40960
	v_permlane32_swap_b32_e32 v220, v222
	v_permlane32_swap_b32_e32 v221, v223
	v_permlane32_swap_b32_e32 v248, v250
	v_permlane32_swap_b32_e32 v249, v251
	s_waitcnt lgkmcnt(0)
; __device__ __forceinline__ void partialSM(f32x16& p0, f32x16& p1, float& m_reg, float& mn, float& alpha) {
;   constexpr float C = SCALE * 1.4426950408889634f;
;   float pmax = p0[0]; for (int r = 1; r < 16; ++r) pmax = fmaxf(pmax, p0[r]); for (int r = 0; r < 16; ++r) pmax = fmaxf(pmax, p1[r]);
;   { auto rr = __builtin_amdgcn_permlane32_swap(__float_as_uint(pmax), __float_as_uint(pmax), false, false);
;     pmax = fmaxf(__uint_as_float(rr[0]), __uint_as_float(rr[1])); }
;   if (__builtin_expect(__all(pmax - m_reg <= THR / SCALE), 1)) { mn = m_reg; alpha = 1.f; }
;   else { mn = fmaxf(m_reg, pmax); alpha = __builtin_amdgcn_exp2f((m_reg - mn) * C); m_reg = mn; }
;   float mnC = -mn * C;
;   for (int r = 0; r < 16; ++r) p0[r] = fmaf(p0[r], C, mnC); for (int r = 0; r < 16; ++r) p1[r] = fmaf(p1[r], C, mnC);
;   for (int r = 0; r < 16; ++r) p0[r] = __builtin_amdgcn_exp2f(p0[r]);
; }
; __device__ __forceinline__ void finishSM(f32x16& p0, f32x16& p1, float alpha, float& l_reg, bf16x8& pa0, bf16x8& pa1, bf16x8& pa2, bf16x8& pa3) {
;   for (int r = 0; r < 16; ++r) p1[r] = __builtin_amdgcn_exp2f(p1[r]);
;   float ps = 0; for (int r = 0; r < 16; ++r) ps += p0[r]; for (int r = 0; r < 16; ++r) ps += p1[r];
;   { auto rr = __builtin_amdgcn_permlane32_swap(__float_as_uint(ps), __float_as_uint(ps), false, false);
;     ps = __uint_as_float(rr[0]) + __uint_as_float(rr[1]); }
;   l_reg = l_reg * alpha + ps;
;     ...
;   PK4(p0, 0, pa0); PK4(p0, 8, pa1); PK4(p1, 0, pa2); PK4(p1, 8, pa3);
;     ...
; }
; __device__ __forceinline__ void qkt(f32x16& p0, f32x16& p1, const bf16* Ks, const bf16x8* qr, int r32, int hi) {
;   p0 = f32x16{}; p1 = f32x16{};
;   for (int d0 = 0; d0 < 8; ++d0) { int cb = (d0 * 16 + hi * 8) * 2;
;     bf16x8 b0 = *reinterpret_cast<const bf16x8*>((const char*)Ks + KSWZ(r32, cb));
;     bf16x8 b1 = *reinterpret_cast<const bf16x8*>((const char*)Ks + KSWZ(32 + r32, cb));
;     p0 = __builtin_amdgcn_mfma_f32_32x32x16_bf16(b0, qr[d0], p0, 0, 0, 0);
;     p1 = __builtin_amdgcn_mfma_f32_32x32x16_bf16(b1, qr[d0], p1, 0, 0, 0); }
; }
; __device__ __forceinline__ int v_st(int k, int c) { const int kk = (k & ~0xC) | ((k & 4) << 1) | ((k & 8) >> 1); return ((kk >> 3) * 4 + (c >> 5)) * 512 + ((kk & 7) * 32 + (c & 31)) * 2; }
; __device__ __forceinline__ int v_rd_base(int lane) { return ((lane & 3) << 3) | (((lane >> 2) & 3) << 6) | (((lane >> 4) & 1) << 5) | (((lane >> 5) & 1) << 8); }
	v_mfma_f32_32x32x16_bf16 v[82:97], v[224:227], v[98:101], v[82:97]
	v_mfma_f32_32x32x16_bf16 v[66:81], v[228:231], v[98:101], v[66:81]
	s_cmpk_gt_u32 s68, 0x80
	s_cselect_b64 s[40:41], -1, 0
	s_cmpk_lt_u32 s68, 0x81
	s_cselect_b32 s4, s67, 0x20c0
	v_or_b32_e32 v130, s4, v181
	v_lshl_or_b32 v134, v130, 8, v183
	v_add_u32_e32 v130, s4, v184
	v_lshl_or_b32 v138, v130, 8, v183
	global_load_dwordx4 v[130:133], v134, s[36:37]
	s_nop 0
	global_load_dwordx4 v[134:137], v134, s[34:35]
	s_nop 0
	global_load_dwordx4 v[142:145], v138, s[36:37]
	s_nop 0
	global_load_dwordx4 v[138:141], v138, s[34:35]
	ds_read_b64_tr_b16 v[228:229], v188 offset:0
	ds_read_b64_tr_b16 v[230:231], v188 offset:0x800
	ds_read_b64_tr_b16 v[232:233], v188 offset:0x1000
	ds_read_b64_tr_b16 v[234:235], v188 offset:0x1800
	ds_read_b64_tr_b16 v[236:237], v188 offset:0x2000
	ds_read_b64_tr_b16 v[238:239], v188 offset:0x2800
	ds_read_b64_tr_b16 v[240:241], v188 offset:0x3000
	ds_read_b64_tr_b16 v[242:243], v188 offset:0x3800
	s_waitcnt lgkmcnt(0)
	s_nop 0
	v_mfma_f32_32x32x16_bf16 v[2:17], v[212:215], v[228:231], v[2:17]
	v_max_f32_e32 v224, v83, v83
	v_max_f32_e32 v225, v82, v82
	v_max_f32_e32 v224, v225, v224
	v_max3_f32 v224, v224, v84, v85
	v_max3_f32 v224, v224, v86, v87
	ds_read_b64_tr_b16 v[228:229], v188 offset:0x200
	ds_read_b64_tr_b16 v[230:231], v188 offset:0xa00
	v_mfma_f32_32x32x16_bf16 v[2:17], v[216:219], v[232:235], v[2:17]
	v_max3_f32 v224, v224, v88, v89
	v_max3_f32 v224, v224, v90, v91
	v_max3_f32 v224, v224, v92, v93
	v_max3_f32 v224, v224, v94, v95
	v_max3_f32 v224, v224, v96, v97
	ds_read_b64_tr_b16 v[232:233], v188 offset:0x1200
	ds_read_b64_tr_b16 v[234:235], v188 offset:0x1a00
	v_mfma_f32_32x32x16_bf16 v[2:17], v[220:223], v[236:239], v[2:17]
	v_max3_f32 v224, v224, v66, v67
	v_max3_f32 v224, v224, v68, v69
	v_max3_f32 v224, v224, v70, v71
	v_max3_f32 v224, v224, v72, v73
	v_max3_f32 v224, v224, v74, v75
	ds_read_b64_tr_b16 v[236:237], v188 offset:0x2200
	ds_read_b64_tr_b16 v[238:239], v188 offset:0x2a00
	ds_read_b64_tr_b16 v[244:245], v188 offset:0x3200
	ds_read_b64_tr_b16 v[246:247], v188 offset:0x3a00
	s_waitcnt lgkmcnt(0)
	v_mfma_f32_32x32x16_bf16 v[2:17], v[248:251], v[240:243], v[2:17]
	v_max3_f32 v224, v224, v76, v77
	v_max3_f32 v224, v224, v78, v79
	v_max3_f32 v224, v224, v80, v81
	v_mov_b32_e32 v225, v224
	s_nop 1
	v_mfma_f32_32x32x16_bf16 v[18:33], v[212:215], v[228:231], v[18:33]
	v_permlane32_swap_b32_e32 v224, v225
	v_max_f32_e32 v225, v225, v225
	v_max_f32_e32 v224, v224, v224
	v_max_f32_e32 v224, v224, v225
	v_max_f32_e32 v226, v164, v164
	ds_read_b64_tr_b16 v[228:229], v188 offset:0x400
	ds_read_b64_tr_b16 v[230:231], v188 offset:0xc00
	v_mfma_f32_32x32x16_bf16 v[18:33], v[216:219], v[232:235], v[18:33]
	v_sub_f32_e32 v225, v224, v164
	v_max_f32_e32 v224, v226, v224
	v_sub_f32_e32 v226, v164, v224
	v_mul_f32_e32 v226, 0x3e0293ee, v226
	v_exp_f32_e32 v226, v226
	ds_read_b64_tr_b16 v[232:233], v188 offset:0x1400
	ds_read_b64_tr_b16 v[234:235], v188 offset:0x1c00
	v_mfma_f32_32x32x16_bf16 v[18:33], v[220:223], v[236:239], v[18:33]
	v_cmp_ge_f32_e32 vcc, s48, v225
	s_cmp_eq_u64 vcc, exec
	s_cselect_b64 s[4:5], -1, 0
	ds_read_b64_tr_b16 v[236:237], v188 offset:0x2400
	ds_read_b64_tr_b16 v[238:239], v188 offset:0x2c00
	ds_read_b64_tr_b16 v[240:241], v188 offset:0x3400
	ds_read_b64_tr_b16 v[242:243], v188 offset:0x3c00
	s_waitcnt lgkmcnt(0)
	v_mfma_f32_32x32x16_bf16 v[18:33], v[248:251], v[244:247], v[18:33]
	v_cndmask_b32_e64 v225, v226, 1.0, s[4:5]
	v_cndmask_b32_e64 v227, v224, v164, s[4:5]
	v_mul_f32_e32 v224, 0xbe0293ee, v227
	v_mfma_f32_32x32x16_bf16 v[50:65], v[212:215], v[228:231], v[50:65]
	v_fmamk_f32 v82, v82, 0x3e0293ee, v224
	v_fmamk_f32 v83, v83, 0x3e0293ee, v224
	v_fmamk_f32 v84, v84, 0x3e0293ee, v224
	ds_read_b64_tr_b16 v[228:229], v188 offset:0x600
	ds_read_b64_tr_b16 v[230:231], v188 offset:0xe00
	v_mfma_f32_32x32x16_bf16 v[50:65], v[216:219], v[232:235], v[50:65]
	v_fmamk_f32 v85, v85, 0x3e0293ee, v224
	v_fmamk_f32 v86, v86, 0x3e0293ee, v224
	v_fmamk_f32 v87, v87, 0x3e0293ee, v224
	ds_read_b64_tr_b16 v[232:233], v188 offset:0x1600
	ds_read_b64_tr_b16 v[234:235], v188 offset:0x1e00
	v_mfma_f32_32x32x16_bf16 v[50:65], v[220:223], v[236:239], v[50:65]
	v_fmamk_f32 v88, v88, 0x3e0293ee, v224
	v_fmamk_f32 v89, v89, 0x3e0293ee, v224
	ds_read_b64_tr_b16 v[236:237], v188 offset:0x2600
	ds_read_b64_tr_b16 v[238:239], v188 offset:0x2e00
	ds_read_b64_tr_b16 v[244:245], v188 offset:0x3600
	ds_read_b64_tr_b16 v[246:247], v188 offset:0x3e00
	s_waitcnt lgkmcnt(0)
	v_mfma_f32_32x32x16_bf16 v[50:65], v[248:251], v[240:243], v[50:65]
	v_fmamk_f32 v90, v90, 0x3e0293ee, v224
	v_fmamk_f32 v91, v91, 0x3e0293ee, v224
	v_mfma_f32_32x32x16_bf16 v[34:49], v[212:215], v[228:231], v[34:49]
	v_fmamk_f32 v92, v92, 0x3e0293ee, v224
	v_fmamk_f32 v93, v93, 0x3e0293ee, v224
	v_mfma_f32_32x32x16_bf16 v[34:49], v[216:219], v[232:235], v[34:49]
	v_fmamk_f32 v94, v94, 0x3e0293ee, v224
	v_fmamk_f32 v95, v95, 0x3e0293ee, v224
	v_mfma_f32_32x32x16_bf16 v[34:49], v[220:223], v[236:239], v[34:49]
	v_fmamk_f32 v96, v96, 0x3e0293ee, v224
	v_fmamk_f32 v97, v97, 0x3e0293ee, v224
	v_mfma_f32_32x32x16_bf16 v[34:49], v[248:251], v[244:247], v[34:49]
	s_barrier
; #define SWAIT() do { if constexpr (SDEPTH == 2) asm volatile("s_waitcnt vmcnt(4)" ::: "memory"); else asm volatile("s_waitcnt vmcnt(0)" ::: "memory"); } while (0)
; #define RESC(a) do { if (__any((a) < 1.f)) { if (hi == 0) al_l[r32] = (a); asm volatile("s_waitcnt lgkmcnt(0)" ::: "memory"); \
;     for (int d = 0; d < 4; ++d) for (int r = 0; r < 16; ++r) o[d][r] *= al_l[crow(r, hi)]; } } while (0)
; template <typename TQ>
; __device__ __forceinline__ void attn_dense_body(const TQ* __restrict__ Qb, const bf16* __restrict__ Kh, const bf16* __restrict__ Vh,
;                                                 unsigned short* __restrict__ Ob, int seq, char* lds) {
;     ...
;     __syncthreads(); SWAIT(); SWRITE(1, SO);
;     RESC(alA); __syncthreads();
	s_waitcnt vmcnt(4)
	v_mov_b32_e32 v162, v225
	v_mov_b32_e32 v208, v227
	v_cmp_gt_f32_e32 vcc, 1.0, v162
	s_waitcnt vmcnt(7)
	ds_write_b128 v191, v[146:149] offset:16384
	s_waitcnt vmcnt(6)
	ds_write_b128 v192, v[150:153] offset:16384
	s_waitcnt vmcnt(5)
	ds_write_b128 v193, v[154:157] offset:49152
	s_waitcnt vmcnt(4)
	ds_write_b128 v194, v[158:161] offset:49152
	s_cbranch_vccz .LBB0_1594
	s_and_saveexec_b64 s[42:43], s[2:3]
	ds_write_b32 v187, v162 offset:128
	s_or_b64 exec, exec, s[42:43]
	s_waitcnt lgkmcnt(0)
	v_add_u32_e32 v158, v182, v186
	ds_read_b128 v[146:149], v158 offset:224
	ds_read_b128 v[150:153], v158 offset:192
	ds_read_b128 v[154:157], v158 offset:160
	ds_read_b128 v[158:161], v158 offset:128
	s_waitcnt lgkmcnt(3)
	v_pk_mul_f32 v[14:15], v[14:15], v[146:147]
	s_waitcnt lgkmcnt(2)
	v_pk_mul_f32 v[10:11], v[10:11], v[150:151]
	s_waitcnt lgkmcnt(1)
	v_pk_mul_f32 v[6:7], v[6:7], v[154:155]
	v_pk_mul_f32 v[16:17], v[16:17], v[148:149]
	v_pk_mul_f32 v[12:13], v[12:13], v[152:153]
	v_pk_mul_f32 v[8:9], v[8:9], v[156:157]
	s_waitcnt lgkmcnt(0)
	v_pk_mul_f32 v[4:5], v[4:5], v[160:161]
	v_pk_mul_f32 v[2:3], v[2:3], v[158:159]
	v_pk_mul_f32 v[30:31], v[30:31], v[146:147]
	v_pk_mul_f32 v[26:27], v[26:27], v[150:151]
	v_pk_mul_f32 v[22:23], v[22:23], v[154:155]
	v_pk_mul_f32 v[32:33], v[32:33], v[148:149]
	v_pk_mul_f32 v[28:29], v[28:29], v[152:153]
	v_pk_mul_f32 v[24:25], v[24:25], v[156:157]
	v_pk_mul_f32 v[20:21], v[20:21], v[160:161]
	v_pk_mul_f32 v[18:19], v[18:19], v[158:159]
	v_pk_mul_f32 v[62:63], v[62:63], v[146:147]
	v_pk_mul_f32 v[58:59], v[58:59], v[150:151]
	v_pk_mul_f32 v[54:55], v[54:55], v[154:155]
	v_pk_mul_f32 v[64:65], v[64:65], v[148:149]
	v_pk_mul_f32 v[60:61], v[60:61], v[152:153]
	v_pk_mul_f32 v[56:57], v[56:57], v[156:157]
	v_pk_mul_f32 v[52:53], v[52:53], v[160:161]
	v_pk_mul_f32 v[50:51], v[50:51], v[158:159]
	v_pk_mul_f32 v[46:47], v[46:47], v[146:147]
	v_pk_mul_f32 v[42:43], v[42:43], v[150:151]
	v_pk_mul_f32 v[38:39], v[38:39], v[154:155]
	v_pk_mul_f32 v[48:49], v[48:49], v[148:149]
	v_pk_mul_f32 v[44:45], v[44:45], v[152:153]
	v_pk_mul_f32 v[40:41], v[40:41], v[156:157]
	v_pk_mul_f32 v[36:37], v[36:37], v[160:161]
	v_pk_mul_f32 v[34:35], v[34:35], v[158:159]
